# phase-2 item table re-balanced with model 0.55*nj+0.67*NS+12
# baseline (speedup 1.0000x reference)
_ZL7idx_tab:
	.short	27
	.short	86
	.short	212
	.short	0
	.short	131
	.short	283
	.short	470
	.short	340
	.short	322
	.short	259
	.short	731
	.short	598
	.short	660
	.short	706
	.short	643
	.short	923
	.short	854
	.short	916
	.short	898
	.short	899
	.short	1243
	.short	1238
	.short	1236
	.short	1090
	.short	1218
	.short	1307
	.short	1302
	.short	1300
	.short	1410
	.short	1346
	.short	1691
	.short	1686
	.short	1748
	.short	1666
	.short	1730
	.short	1883
	.short	2006
	.short	2004
	.short	1922
	.short	1986
	.short	155
	.short	150
	.short	20
	.short	130
	.short	3
	.short	475
	.short	342
	.short	468
	.short	450
	.short	451
	.short	539
	.short	534
	.short	724
	.short	705
	.short	577
	.short	859
	.short	790
	.short	980
	.short	962
	.short	963
	.short	1115
	.short	1110
	.short	1044
	.short	1154
	.short	1219
	.short	1435
	.short	1494
	.short	1364
	.short	1472
	.short	1411
	.short	1755
	.short	1622
	.short	1556
	.short	1603
	.short	1537
	.short	1947
	.short	1814
	.short	1876
	.short	1794
	.short	1795
	.short	32
	.short	13
	.short	12
	.short	69
	.short	65535
	.short	224
	.short	397
	.short	332
	.short	261
	.short	65535
	.short	352
	.short	653
	.short	716
	.short	517
	.short	65535
	.short	416
	.short	973
	.short	844
	.short	901
	.short	65535
	.short	608
	.short	1101
	.short	1036
	.short	1029
	.short	65535
	.short	672
	.short	1421
	.short	1356
	.short	1285
	.short	65535
	.short	800
	.short	1549
	.short	1676
	.short	1669
	.short	65535
	.short	928
	.short	1805
	.short	1868
	.short	1861
	.short	65535
	.short	96
	.short	141
	.short	76
	.short	5
	.short	65535
	.short	160
	.short	333
	.short	396
	.short	389
	.short	65535
	.short	288
	.short	525
	.short	524
	.short	645
	.short	65535
	.short	480
	.short	845
	.short	908
	.short	965
	.short	65535
	.short	544
	.short	1229
	.short	1164
	.short	1221
	.short	65535
	.short	736
	.short	1293
	.short	1420
	.short	1413
	.short	65535
	.short	864
	.short	1677
	.short	1740
	.short	1733
	.short	65535
	.short	992
	.short	1997
	.short	1996
	.short	1989
	.short	65535
	.short	31
	.short	77
	.short	204
	.short	71
	.short	65535
	.short	351
	.short	269
	.short	268
	.short	263
	.short	65535
	.short	671
	.short	589
	.short	652
	.short	519
	.short	65535
	.short	863
	.short	781
	.short	972
	.short	775
	.short	65535
	.short	1119
	.short	1037
	.short	1100
	.short	1223
	.short	65535
	.short	1311
	.short	1357
	.short	1292
	.short	1479
	.short	65535
	.short	1567
	.short	1613
	.short	1612
	.short	1671
	.short	65535
	.short	1887
	.short	1869
	.short	1804
	.short	1863
	.short	65535
	.short	223
	.short	205
	.short	140
	.short	199
	.short	65535
	.short	479
	.short	461
	.short	460
	.short	327
	.short	65535
	.short	543
	.short	717
	.short	588
	.short	583
	.short	65535
	.short	927
	.short	909
	.short	780
	.short	903
	.short	65535
	.short	1183
	.short	1165
	.short	1228
	.short	1159
	.short	65535
	.short	1439
	.short	1485
	.short	1484
	.short	1351
	.short	65535
	.short	1631
	.short	1741
	.short	1548
	.short	1607
	.short	65535
	.short	1951
	.short	1933
	.short	1932
	.short	1927
	.short	65535
	.short	95
	.short	206
	.short	11
	.short	6
	.short	65535
	.short	287
	.short	462
	.short	459
	.short	390
	.short	65535
	.short	735
	.short	718
	.short	523
	.short	646
	.short	65535
	.short	799
	.short	782
	.short	779
	.short	774
	.short	65535
	.short	1247
	.short	1102
	.short	1035
	.short	1030
	.short	65535
	.short	1503
	.short	1422
	.short	1355
	.short	1350
	.short	65535
	.short	1695
	.short	1742
	.short	1547
	.short	1606
	.short	65535
	.short	2015
	.short	1870
	.short	1931
	.short	1798
	.short	65535
	.short	159
	.short	14
	.short	75
	.short	134
	.short	65535
	.short	415
	.short	270
	.short	267
	.short	262
	.short	65535
	.short	607
	.short	654
	.short	587
	.short	710
	.short	65535
	.short	991
	.short	910
	.short	971
	.short	838
	.short	65535
	.short	1055
	.short	1166
	.short	1163
	.short	1158
	.short	65535
	.short	1375
	.short	1486
	.short	1483
	.short	1414
	.short	65535
	.short	1759
	.short	1614
	.short	1611
	.short	1670
	.short	65535
	.short	1823
	.short	1806
	.short	1867
	.short	1926
	.short	65535
	.short	94
	.short	23
	.short	214
	.short	65535
	.short	65535
	.short	286
	.short	343
	.short	278
	.short	65535
	.short	65535
	.short	606
	.short	663
	.short	726
	.short	65535
	.short	65535
	.short	798
	.short	919
	.short	918
	.short	65535
	.short	65535
	.short	1182
	.short	1111
	.short	1046
	.short	65535
	.short	65535
	.short	1374
	.short	1367
	.short	1366
	.short	65535
	.short	65535
	.short	1566
	.short	1751
	.short	1750
	.short	65535
	.short	65535
	.short	1950
	.short	2007
	.short	1878
	.short	65535
	.short	65535
	.short	30
	.short	215
	.short	22
	.short	65535
	.short	65535
	.short	350
	.short	407
	.short	406
	.short	65535
	.short	65535
	.short	734
	.short	727
	.short	662
	.short	65535
	.short	65535
	.short	862
	.short	791
	.short	982
	.short	65535
	.short	65535
	.short	1054
	.short	1047
	.short	1174
	.short	65535
	.short	65535
	.short	1310
	.short	1495
	.short	1430
	.short	65535
	.short	65535
	.short	1694
	.short	1687
	.short	1558
	.short	65535
	.short	65535
	.short	2014
	.short	1879
	.short	1942
	.short	65535
	.short	65535
	.short	158
	.short	219
	.short	207
	.short	65
	.short	65535
	.short	414
	.short	411
	.short	463
	.short	321
	.short	65535
	.short	670
	.short	603
	.short	591
	.short	704
	.short	65535
	.short	990
	.short	987
	.short	783
	.short	770
	.short	65535
	.short	1246
	.short	1051
	.short	1039
	.short	1025
	.short	65535
	.short	1438
	.short	1371
	.short	1359
	.short	1282
	.short	65535
	.short	1758
	.short	1627
	.short	1743
	.short	1729
	.short	65535
	.short	1822
	.short	2011
	.short	1871
	.short	1985
	.short	65535
	.short	222
	.short	91
	.short	79
	.short	193
	.short	65535
	.short	478
	.short	347
	.short	335
	.short	387
	.short	65535
	.short	542
	.short	667
	.short	655
	.short	513
	.short	65535
	.short	926
	.short	795
	.short	847
	.short	834
	.short	65535
	.short	1118
	.short	1179
	.short	1167
	.short	1153
	.short	65535
	.short	1502
	.short	1499
	.short	1423
	.short	1344
	.short	65535
	.short	1630
	.short	1563
	.short	1679
	.short	1667
	.short	65535
	.short	1886
	.short	1819
	.short	1935
	.short	1857
	.short	65535
	.short	93
	.short	151
	.short	147
	.short	194
	.short	65535
	.short	477
	.short	471
	.short	339
	.short	448
	.short	65535
	.short	541
	.short	599
	.short	723
	.short	641
	.short	65535
	.short	925
	.short	855
	.short	979
	.short	897
	.short	65535
	.short	1245
	.short	1175
	.short	1043
	.short	1089
	.short	65535
	.short	1309
	.short	1303
	.short	1427
	.short	1281
	.short	65535
	.short	1757
	.short	1559
	.short	1683
	.short	1602
	.short	65535
	.short	1885
	.short	1943
	.short	1811
	.short	1921
	.short	65535
	.short	29
	.short	87
	.short	83
	.short	64
	.short	65535
	.short	413
	.short	279
	.short	467
	.short	386
	.short	65535
	.short	733
	.short	535
	.short	659
	.short	512
	.short	65535
	.short	797
	.short	983
	.short	851
	.short	768
	.short	65535
	.short	1053
	.short	1239
	.short	1107
	.short	1217
	.short	65535
	.short	1437
	.short	1431
	.short	1363
	.short	1475
	.short	65535
	.short	1693
	.short	1623
	.short	1619
	.short	1539
	.short	65535
	.short	1821
	.short	1815
	.short	1939
	.short	1793
	.short	65535
	.short	157
	.short	85
	.short	211
	.short	195
	.short	128
	.short	285
	.short	469
	.short	403
	.short	258
	.short	257
	.short	669
	.short	725
	.short	595
	.short	707
	.short	576
	.short	861
	.short	853
	.short	915
	.short	771
	.short	960
	.short	1181
	.short	1173
	.short	1171
	.short	1155
	.short	1091
	.short	1373
	.short	1365
	.short	1299
	.short	1283
	.short	1280
	.short	1629
	.short	1621
	.short	1555
	.short	1731
	.short	1600
	.short	1949
	.short	1813
	.short	1875
	.short	1923
	.short	1792
	.short	221
	.short	21
	.short	19
	.short	2
	.short	192
	.short	349
	.short	405
	.short	275
	.short	323
	.short	385
	.short	605
	.short	661
	.short	531
	.short	578
	.short	579
	.short	989
	.short	789
	.short	787
	.short	835
	.short	833
	.short	1117
	.short	1045
	.short	1235
	.short	1026
	.short	1024
	.short	1501
	.short	1493
	.short	1491
	.short	1409
	.short	1408
	.short	1565
	.short	1685
	.short	1747
	.short	1538
	.short	1728
	.short	2013
	.short	2005
	.short	2003
	.short	1987
	.short	1920
	.short	28
	.short	142
	.short	202
	.short	70
	.short	65535
	.short	284
	.short	398
	.short	458
	.short	326
	.short	65535
	.short	540
	.short	526
	.short	650
	.short	518
	.short	65535
	.short	988
	.short	846
	.short	778
	.short	966
	.short	65535
	.short	1244
	.short	1038
	.short	1162
	.short	1222
	.short	65535
	.short	1500
	.short	1358
	.short	1290
	.short	1478
	.short	65535
	.short	1564
	.short	1678
	.short	1674
	.short	1734
	.short	65535
	.short	1948
	.short	1934
	.short	1866
	.short	1862
	.short	65535
	.short	92
	.short	78
	.short	138
	.short	198
	.short	65535
	.short	412
	.short	334
	.short	330
	.short	454
	.short	65535
	.short	668
	.short	590
	.short	714
	.short	582
	.short	65535
	.short	796
	.short	974
	.short	842
	.short	902
	.short	65535
	.short	1052
	.short	1230
	.short	1034
	.short	1094
	.short	65535
	.short	1308
	.short	1294
	.short	1482
	.short	1286
	.short	65535
	.short	1628
	.short	1550
	.short	1738
	.short	1542
	.short	65535
	.short	1884
	.short	1998
	.short	1994
	.short	1990
	.short	65535
	.short	220
	.short	149
	.short	84
	.short	66
	.short	1
	.short	476
	.short	277
	.short	404
	.short	256
	.short	449
	.short	732
	.short	597
	.short	596
	.short	642
	.short	514
	.short	860
	.short	917
	.short	852
	.short	769
	.short	961
	.short	1116
	.short	1237
	.short	1172
	.short	1027
	.short	1152
	.short	1436
	.short	1429
	.short	1428
	.short	1347
	.short	1345
	.short	1756
	.short	1557
	.short	1684
	.short	1536
	.short	1665
	.short	2012
	.short	1877
	.short	1812
	.short	1858
	.short	1856
	.short	156
	.short	213
	.short	148
	.short	67
	.short	129
	.short	348
	.short	341
	.short	276
	.short	384
	.short	320
	.short	604
	.short	533
	.short	532
	.short	515
	.short	640
	.short	924
	.short	981
	.short	788
	.short	896
	.short	832
	.short	1180
	.short	1109
	.short	1108
	.short	1088
	.short	1216
	.short	1372
	.short	1301
	.short	1492
	.short	1474
	.short	1473
	.short	1692
	.short	1749
	.short	1620
	.short	1664
	.short	1601
	.short	1820
	.short	1941
	.short	1940
	.short	1859
	.short	1984
	.short	210
	.short	146
	.short	10
	.short	73
	.short	65535
	.short	466
	.short	338
	.short	266
	.short	393
	.short	65535
	.short	658
	.short	530
	.short	522
	.short	713
	.short	65535
	.short	850
	.short	978
	.short	970
	.short	777
	.short	65535
	.short	1234
	.short	1042
	.short	1226
	.short	1225
	.short	65535
	.short	1426
	.short	1490
	.short	1354
	.short	1353
	.short	65535
	.short	1682
	.short	1746
	.short	1610
	.short	1737
	.short	65535
	.short	1810
	.short	1874
	.short	1930
	.short	1993
	.short	65535
	.short	82
	.short	18
	.short	74
	.short	137
	.short	65535
	.short	402
	.short	274
	.short	394
	.short	265
	.short	65535
	.short	722
	.short	594
	.short	586
	.short	649
	.short	65535
	.short	914
	.short	786
	.short	906
	.short	905
	.short	65535
	.short	1106
	.short	1170
	.short	1098
	.short	1161
	.short	65535
	.short	1362
	.short	1298
	.short	1418
	.short	1417
	.short	65535
	.short	1618
	.short	1554
	.short	1546
	.short	1545
	.short	65535
	.short	2002
	.short	1938
	.short	1802
	.short	1801
	.short	65535
	.short	152
	.short	17
	.short	200
	.short	133
	.short	65535
	.short	344
	.short	337
	.short	392
	.short	325
	.short	65535
	.short	600
	.short	529
	.short	520
	.short	709
	.short	65535
	.short	792
	.short	849
	.short	776
	.short	837
	.short	65535
	.short	1112
	.short	1169
	.short	1160
	.short	1157
	.short	65535
	.short	1368
	.short	1489
	.short	1288
	.short	1477
	.short	65535
	.short	1624
	.short	1553
	.short	1608
	.short	1541
	.short	65535
	.short	1816
	.short	1873
	.short	1864
	.short	1925
	.short	65535
	.short	88
	.short	209
	.short	136
	.short	197
	.short	65535
	.short	280
	.short	465
	.short	456
	.short	453
	.short	65535
	.short	664
	.short	657
	.short	584
	.short	581
	.short	65535
	.short	920
	.short	913
	.short	840
	.short	773
	.short	65535
	.short	1048
	.short	1105
	.short	1032
	.short	1093
	.short	65535
	.short	1432
	.short	1297
	.short	1480
	.short	1349
	.short	65535
	.short	1688
	.short	1681
	.short	1736
	.short	1605
	.short	65535
	.short	1880
	.short	1809
	.short	1800
	.short	1797
	.short	65535
	.short	218
	.short	143
	.short	139
	.short	7
	.short	65535
	.short	346
	.short	399
	.short	395
	.short	391
	.short	65535
	.short	602
	.short	527
	.short	715
	.short	647
	.short	65535
	.short	858
	.short	911
	.short	907
	.short	967
	.short	65535
	.short	1178
	.short	1103
	.short	1227
	.short	1031
	.short	65535
	.short	1370
	.short	1487
	.short	1291
	.short	1415
	.short	65535
	.short	1754
	.short	1615
	.short	1739
	.short	1735
	.short	65535
	.short	1946
	.short	1999
	.short	1803
	.short	1991
	.short	65535
	.short	90
	.short	15
	.short	203
	.short	135
	.short	65535
	.short	410
	.short	271
	.short	331
	.short	455
	.short	65535
	.short	730
	.short	719
	.short	651
	.short	711
	.short	65535
	.short	922
	.short	975
	.short	843
	.short	839
	.short	65535
	.short	1114
	.short	1231
	.short	1099
	.short	1095
	.short	65535
	.short	1306
	.short	1295
	.short	1419
	.short	1287
	.short	65535
	.short	1626
	.short	1551
	.short	1675
	.short	1543
	.short	65535
	.short	2010
	.short	1807
	.short	1995
	.short	1799
	.short	65535
	.short	25
	.short	144
	.short	201
	.short	132
	.short	65535
	.short	281
	.short	464
	.short	457
	.short	324
	.short	65535
	.short	665
	.short	528
	.short	585
	.short	708
	.short	65535
	.short	857
	.short	784
	.short	969
	.short	836
	.short	65535
	.short	1241
	.short	1104
	.short	1033
	.short	1028
	.short	65535
	.short	1305
	.short	1424
	.short	1289
	.short	1284
	.short	65535
	.short	1753
	.short	1744
	.short	1673
	.short	1604
	.short	65535
	.short	1945
	.short	1936
	.short	1865
	.short	1988
	.short	65535
	.short	89
	.short	16
	.short	9
	.short	4
	.short	65535
	.short	473
	.short	272
	.short	329
	.short	260
	.short	65535
	.short	729
	.short	720
	.short	521
	.short	516
	.short	65535
	.short	985
	.short	976
	.short	841
	.short	964
	.short	65535
	.short	1177
	.short	1232
	.short	1097
	.short	1220
	.short	65535
	.short	1433
	.short	1296
	.short	1481
	.short	1412
	.short	65535
	.short	1689
	.short	1680
	.short	1609
	.short	1732
	.short	65535
	.short	1817
	.short	2000
	.short	1929
	.short	1860
	.short	65535
	.short	217
	.short	24
	.short	81
	.short	65535
	.short	65535
	.short	409
	.short	472
	.short	401
	.short	65535
	.short	65535
	.short	537
	.short	536
	.short	721
	.short	65535
	.short	65535
	.short	793
	.short	984
	.short	977
	.short	65535
	.short	65535
	.short	1113
	.short	1176
	.short	1041
	.short	65535
	.short	65535
	.short	1369
	.short	1304
	.short	1425
	.short	65535
	.short	65535
	.short	1561
	.short	1560
	.short	1745
	.short	65535
	.short	65535
	.short	2009
	.short	1944
	.short	1937
	.short	65535
	.short	65535
	.short	153
	.short	216
	.short	145
	.short	65535
	.short	65535
	.short	345
	.short	408
	.short	273
	.short	65535
	.short	65535
	.short	601
	.short	728
	.short	593
	.short	65535
	.short	65535
	.short	921
	.short	856
	.short	785
	.short	65535
	.short	65535
	.short	1049
	.short	1240
	.short	1233
	.short	65535
	.short	65535
	.short	1497
	.short	1496
	.short	1361
	.short	65535
	.short	65535
	.short	1625
	.short	1752
	.short	1617
	.short	65535
	.short	65535
	.short	1881
	.short	2008
	.short	2001
	.short	65535
	.short	65535
	.short	26
	.short	80
	.short	72
	.short	196
	.short	65535
	.short	282
	.short	400
	.short	328
	.short	452
	.short	65535
	.short	666
	.short	656
	.short	712
	.short	580
	.short	65535
	.short	986
	.short	848
	.short	968
	.short	772
	.short	65535
	.short	1242
	.short	1040
	.short	1096
	.short	1156
	.short	65535
	.short	1498
	.short	1360
	.short	1352
	.short	1476
	.short	65535
	.short	1562
	.short	1616
	.short	1544
	.short	1668
	.short	65535
	.short	1818
	.short	1872
	.short	1928
	.short	1924
	.short	65535
	.short	154
	.short	208
	.short	8
	.short	68
	.short	65535
	.short	474
	.short	336
	.short	264
	.short	388
	.short	65535
	.short	538
	.short	592
	.short	648
	.short	644
	.short	65535
	.short	794
	.short	912
	.short	904
	.short	900
	.short	65535
	.short	1050
	.short	1168
	.short	1224
	.short	1092
	.short	65535
	.short	1434
	.short	1488
	.short	1416
	.short	1348
	.short	65535
	.short	1690
	.short	1552
	.short	1672
	.short	1540
	.short	65535
	.short	1882
	.short	1808
	.short	1992
	.short	1796
	.short	65535
	.size	_ZL7idx_tab, 2560

	.type	__hip_cuid_794236f6d9ab0dff,@object
